# v31 + GEMM phase prologue: the 3 later first-K-pair STAGEs issued before the first wait (vmcnt 4 -> 10) so both DMA batches share one round trip
# speedup vs baseline: 1.0049x; 1.0049x over previous
; #define PG8_STAGE(bufoff, gbase, voff) do { _Pragma("unroll") for (int _i = 0; _i < 2; ++_i) \
;     __builtin_amdgcn_global_load_lds((const unsigned*)((const char*)(gbase) + (voff)[_i]), (LAS unsigned*)(lds + (bufoff) + ldsw + _i * 8192), 16, 0, 0); } while (0)
; #define PG8_WAIT_V(n) asm volatile("s_waitcnt vmcnt(" #n ")" ::: "memory")
; #define PG8_BAR __builtin_amdgcn_s_barrier()
; template <class Epi>
; __device__ __forceinline__ void gemm_phase(LAS unsigned char* lds, const Gemm g, const Epi& E) {
;     ...
;   const char* cA = (const char*)(cur.w ? g.A2 : g.A) + (size_t)cur.pm * tstepA; const char* cB = (const char*)(cur.w ? g.Bt2 : g.Bt) + (size_t)cur.pn * tstepB;
;   PG8_STAGE(PG8_SB(0, 0), cB, voffB); PG8_STAGE(PG8_SA(0, 0), cA, voffA); PG8_STAGE(PG8_SB(0, 1), cB + hstepB, voffB); PG8_STAGE(PG8_SA(0, 1), cA + hstepA, voffA);
;   if (wr == 1) PG8_BAR;
;   PG8_WAIT_V(4); PG8_BAR;
;   PG8_STAGE(PG8_SB(1, 0), cB + kstep, voffB); PG8_STAGE(PG8_SA(1, 0), cA + kstep, voffA); PG8_STAGE(PG8_SB(1, 1), cB + hstepB + kstep, voffB);
;   PG8_WAIT_V(6); PG8_BAR;
.LBB0_563:
	s_andn2_b64 vcc, exec, s[36:37]
	s_cbranch_vccnz .LBB0_1255
	v_bfe_i32 v2, v18, 27, 1
	v_lshlrev_b32_e32 v0, 4, v18
	v_lshrrev_b32_e32 v2, 22, v2
	v_add_u32_e32 v2, v0, v2
	v_and_b32_e32 v2, 0xfffffc00, v2
	v_sub_u32_e32 v2, v0, v2
	v_ashrrev_i32_e32 v1, 31, v18
	v_lshrrev_b32_e32 v3, 4, v2
	v_lshrrev_b32_e32 v1, 26, v1
	v_bitop3_b32 v2, v3, v2, 32 bitop3:0x6c
	v_add_u32_e32 v1, v18, v1
	v_ashrrev_i32_e32 v4, 31, v2
	v_ashrrev_i32_e32 v1, 6, v1
	v_lshrrev_b32_e32 v4, 26, v4
	v_lshlrev_b32_e32 v3, 3, v1
	v_add_u32_e32 v4, v2, v4
	v_and_b32_e32 v3, -16, v3
	v_ashrrev_i32_e32 v5, 6, v4
	v_lshlrev_b32_e32 v1, 5, v1
	v_add_u32_e32 v3, v5, v3
	v_and_b32_e32 v12, 32, v1
	v_and_b32_e32 v1, 0xc0, v4
	v_sub_u32_e32 v1, v2, v1
	v_lshlrev_b32_e32 v2, 1, v3
	v_lshrrev_b32_e32 v4, 2, v3
	v_and_b32_e32 v5, 3, v5
	s_mov_b32 s1, 0x7fffffe0
	v_ashrrev_i16_sdwa v1, v230, sext(v1) dst_sel:DWORD dst_unused:UNUSED_PAD src0_sel:DWORD src1_sel:BYTE_0
	v_and_b32_e32 v2, 24, v2
	v_and_b32_e32 v4, 4, v4
	v_and_or_b32 v5, v3, s1, v5
	v_bfe_i32 v13, v1, 0, 16
	v_or3_b32 v2, v5, v4, v2
	v_add_u32_e32 v1, v12, v13
	v_mul_lo_u32 v14, v3, s20
	v_mul_lo_u32 v2, v2, s29
	v_add_u32_e32 v0, 0x2000, v0
	v_add_lshl_u32 v138, v1, v14, 1
	v_add_lshl_u32 v132, v2, v1, 1
	v_ashrrev_i32_e32 v1, 31, v0
	v_lshrrev_b32_e32 v1, 22, v1
	v_add_u32_e32 v1, v0, v1
	v_ashrrev_i32_e32 v1, 10, v1
	v_mul_i32_i24_e32 v2, 0x400, v1
	v_sub_u32_e32 v0, v0, v2
	v_lshrrev_b32_e32 v2, 4, v0
	v_bitop3_b32 v0, v2, v0, 32 bitop3:0x6c
	s_lshl_b32 s56, s20, 8
	v_ashrrev_i32_e32 v3, 31, v0
	s_lshl_b64 s[30:31], s[56:57], 1
	s_ashr_i32 s2, s75, 31
	v_lshrrev_b32_e32 v3, 26, v3
	s_mul_i32 s2, s30, s2
	s_mul_hi_u32 s3, s30, s75
	v_lshlrev_b32_e32 v2, 3, v1
	v_add_u32_e32 v3, v0, v3
	s_add_i32 s2, s3, s2
	s_bfe_u32 s3, s20, 0x10017
	v_and_b32_e32 v2, -16, v2
	v_ashrrev_i32_e32 v4, 6, v3
	s_mul_i32 s3, s3, s75
	v_add_u32_e32 v2, v4, v2
	s_lshl_b32 s96, s29, 9
	s_add_i32 s3, s2, s3
	s_ashr_i32 s2, s53, 31
	s_ashr_i32 s0, s35, 6
	v_and_b32_e32 v4, 3, v4
	v_mul_lo_u32 v17, v2, s20
	s_mul_i32 s2, s96, s2
	s_mul_hi_u32 s20, s96, s53
	v_and_or_b32 v4, v2, s1, v4
	s_ashr_i32 s1, s35, 8
	s_lshl_b32 s95, s29, 8
	s_lshl_b32 s97, s0, 10
	s_add_i32 s20, s20, s2
	v_lshlrev_b32_e32 v1, 5, v1
	s_cmp_eq_u32 s12, 0
	v_and_b32_e32 v15, 32, v1
	v_and_b32_e32 v1, 0xc0, v3
	s_cselect_b32 s26, s62, s42
	s_mul_i32 s27, s96, s53
	v_sub_u32_e32 v0, v0, v1
	v_lshlrev_b32_e32 v1, 1, v2
	v_lshrrev_b32_e32 v3, 2, v2
	v_writelane_b32 v255, s35, 29
	s_cselect_b32 s21, s63, s43
	s_cselect_b32 s35, s61, s71
	s_cselect_b32 s36, s60, s70
	s_add_u32 s26, s26, s27
	v_ashrrev_i16_sdwa v0, v230, sext(v0) dst_sel:DWORD dst_unused:UNUSED_PAD src0_sel:DWORD src1_sel:BYTE_0
	v_and_b32_e32 v1, 24, v1
	v_and_b32_e32 v3, 4, v3
	s_addc_u32 s27, s21, s20
	s_add_i32 s84, s97, 0
	v_bfe_i32 v16, v0, 0, 16
	v_or3_b32 v1, v4, v3, v1
	s_add_i32 m0, s84, 0x10000
	v_add_u32_e32 v0, v15, v16
	v_mul_lo_u32 v1, v1, s29
	s_mul_i32 s2, s30, s75
	global_load_lds_dwordx4 v132, s[26:27]
	s_add_i32 m0, s84, 0x12000
	v_add_lshl_u32 v142, v1, v0, 1
	s_add_u32 s2, s36, s2
	global_load_lds_dwordx4 v142, s[26:27]
	s_addc_u32 s3, s35, s3
	s_mov_b32 m0, s84
	s_add_i32 s85, s84, 0x2000
	v_add_lshl_u32 v140, v0, v17, 1
	global_load_lds_dwordx4 v138, s[2:3]
	s_mov_b32 m0, s85
	s_add_u32 s20, s26, s95
	global_load_lds_dwordx4 v140, s[2:3]
	s_addc_u32 s21, s27, 0
	s_add_i32 m0, s84, 0x14000
	v_mov_b32_e32 v143, v133
	global_load_lds_dwordx4 v132, s[20:21]
	s_add_i32 m0, s84, 0x16000
	v_lshl_add_u64 v[8:9], s[20:21], 0, v[132:133]
	v_lshl_add_u64 v[10:11], s[20:21], 0, v[142:143]
	global_load_lds_dwordx4 v142, s[20:21]
	s_add_u32 s20, s2, s56
	s_addc_u32 s21, s3, 0
	s_add_i32 s86, s84, 0x4000
	s_mov_b32 m0, s86
	s_add_i32 s87, s84, 0x6000
	global_load_lds_dwordx4 v138, s[20:21]
	s_mov_b32 m0, s87
	v_mov_b32_e32 v139, v133
	global_load_lds_dwordx4 v140, s[20:21]
	v_mov_b32_e32 v141, v133
	v_lshl_add_u64 v[0:1], s[26:27], 0, v[132:133]
	v_lshl_add_u64 v[2:3], s[26:27], 0, v[142:143]
	v_lshl_add_u64 v[4:5], s[2:3], 0, v[138:139]
	v_lshl_add_u64 v[6:7], s[2:3], 0, v[140:141]
	s_add_i32 m0, s84, 0x18000
	v_lshl_add_u64 v[0:1], v[0:1], 0, s[22:23]
	global_load_lds_dwordx4 v[0:1], off
	v_lshl_add_u64 v[0:1], v[2:3], 0, s[22:23]
	s_add_i32 m0, s84, 0x1a000
	s_add_i32 s74, s84, 0x8000
	global_load_lds_dwordx4 v[0:1], off
	v_lshl_add_u64 v[0:1], v[4:5], 0, s[22:23]
	s_mov_b32 m0, s74
	s_add_i32 s78, s84, 0xa000
	global_load_lds_dwordx4 v[0:1], off
	v_lshl_add_u64 v[0:1], v[6:7], 0, s[22:23]
	s_mov_b32 m0, s78
	s_lshl_b32 s88, s28, 3
	global_load_lds_dwordx4 v[0:1], off
	s_add_i32 m0, s84, 0x1c000
	v_lshl_add_u64 v[0:1], v[8:9], 0, s[22:23]
	global_load_lds_dwordx4 v[0:1], off
	v_lshl_add_u64 v[0:1], v[10:11], 0, s[22:23]
	s_add_i32 m0, s84, 0x1e000
	v_lshrrev_b32_e32 v20, 1, v18
	global_load_lds_dwordx4 v[0:1], off
	s_cmp_lg_u32 s1, 1
	s_cbranch_scc1 .LBB0_566
	s_barrier
.LBB0_566:
	s_waitcnt vmcnt(10)
	s_barrier
	v_cvt_f32_u32_e32 v0, s88
	v_and_b32_e32 v20, 24, v20
	v_and_b32_e32 v19, 15, v18
	v_lshlrev_b32_e32 v21, 1, v20
	v_rcp_iflag_f32_e32 v0, v0
	v_lshlrev_b32_e32 v18, 2, v18
	s_lshl_b32 s0, s0, 5
	v_lshl_or_b32 v172, s1, 6, v19
	v_mul_f32_e32 v0, 0x4f7ffffe, v0
	v_cvt_u32_f32_e32 v0, v0
	v_lshl_or_b32 v19, v19, 6, v21
	s_lshl_b32 s1, s1, 13
	v_and_b32_e32 v18, 32, v18
	s_and_b32 s0, s0, 0x60
	v_bitop3_b32 v21, v19, s1, v18 bitop3:0xde
	s_lshl_b32 s1, s0, 7
	v_bitop3_b32 v173, v19, s1, v18 bitop3:0xde
	s_lshr_b32 s1, s34, 3
	v_writelane_b32 v255, s1, 23
	s_add_i32 s77, s1, 1
	v_readfirstlane_b32 s1, v0
	v_add_u32_e32 v0, v14, v12
	v_or_b32_e32 v174, s0, v20
	s_sub_i32 s0, 0, s88
	v_add_lshl_u32 v0, v0, v13, 1
	v_mov_b32_e32 v1, v133
	s_waitcnt vmcnt(6)
	s_mul_i32 s0, s0, s1
	v_lshl_add_u64 v[144:145], s[56:57], 0, v[0:1]
	v_add_u32_e32 v0, v17, v15
	s_lshr_b32 s72, s29, 6
	s_mul_hi_u32 s0, s1, s0
	v_add_lshl_u32 v0, v0, v16, 1
	s_ashr_i32 s73, s90, 31
	v_mov_b32_e32 v137, v133
	s_mov_b32 s35, s57
	s_and_b32 s79, s34, 7
	s_add_i32 s89, s72, -2
	s_mov_b32 s48, 0
	s_add_i32 s49, s1, s0
	v_lshl_add_u64 v[146:147], s[56:57], 0, v[0:1]
	v_add_u32_e32 v175, 0, v21
	s_barrier
	s_mov_b32 s32, 0
	s_branch .LBB0_568
